# wout epilogue: all 16 residual (xb) loads issued up front into dead fragment VGPRs, counted vmcnt(15) waits instead of 16 serial load+vmcnt(0) store-drains
# speedup vs baseline: 1.0835x; 1.0212x over previous
;   __device__ __forceinline__ void operator()(const f32x4 (&acc)[2][2][4][2], const g8::Unit& u, int ui, int wr, int wc, int fr, int fq) const {
; #pragma unroll
;     for (int ai = 0; ai < 2; ++ai)
; #pragma unroll
;       for (int m = 0; m < 4; ++m) {
;         const size_t row = (size_t)u.pm * 256 + 128 * ai + 64 * wr + 16 * m + fr;
;         const size_t base = row * DM + 256 * u.pn + 32 * wc + 8 * fq;
;         float ss = 0.f;
; #pragma unroll
;         for (int bj = 0; bj < 2; ++bj) {
;           const size_t idx = base + 128 * bj;
;           const h16x8 xv = *(const h16x8*)(xb + idx);
;           f32x4 x0 = acc[ai][bj][m][0], x1 = acc[ai][bj][m][1];
; #pragma unroll
;           for (int j = 0; j < 4; ++j) { x0[j] += (float)xv[j]; x1[j] += (float)xv[4 + j]; ss += x0[j] * x0[j] + x1[j] * x1[j]; }
;           if (final_out) {
;             __builtin_nontemporal_store(x0, (f32x4*)(xo + idx));
;             __builtin_nontemporal_store(x1, (f32x4*)(xo + idx + 4));
;           } else {
;             *(h16x8*)(xb + idx) = pack8(x0, x1);
.LBB0_2381:
	s_ashr_i32 s23, s22, 31
	s_lshl_b64 s[20:21], s[22:23], 8
	v_and_b32_e32 v156, 64, v199
	v_lshl_add_u64 v[2:3], s[20:21], 0, v[136:137]
	s_lshl_b32 s3, s2, 8
	v_xor_b32_e32 v0, 32, v199
	v_add_u32_e32 v156, 64, v156
	s_ashr_i32 s13, s3, 31
	v_cmp_lt_i32_e32 vcc, v0, v156
	v_lshlrev_b64 v[156:157], 11, v[2:3]
	v_mov_b32_e32 v155, s13
	v_or_b32_e32 v154, s3, v138
	v_lshl_add_u64 v[156:157], s[0:1], 0, v[156:157]
	v_lshl_add_u64 v[156:157], v[154:155], 1, v[156:157]
	v_cndmask_b32_e32 v0, v199, v0, vcc
	v_lshlrev_b32_e32 v0, 2, v0
	s_lshl_b32 s20, s2, 2
	s_ashr_i32 s21, s20, 31
	global_load_dwordx4 v[166:169], v[156:157], off
	global_load_dwordx4 v[170:173], v[156:157], off offset:256
	s_mov_b32 s3, 0
	s_mov_b32 s2, 0x8000
	v_lshl_add_u64 v[242:243], v[156:157], 0, s[2:3]
	global_load_dwordx4 v[174:177], v[242:243], off
	global_load_dwordx4 v[178:181], v[242:243], off offset:256
	s_mov_b32 s2, 0x10000
	v_lshl_add_u64 v[244:245], v[156:157], 0, s[2:3]
	global_load_dwordx4 v[182:185], v[244:245], off
	global_load_dwordx4 v[186:189], v[244:245], off offset:256
	s_mov_b32 s2, 0x18000
	v_lshl_add_u64 v[242:243], v[156:157], 0, s[2:3]
	global_load_dwordx4 v[202:205], v[242:243], off
	global_load_dwordx4 v[206:209], v[242:243], off offset:256
	s_mov_b32 s2, 0x40000
	v_lshl_add_u64 v[244:245], v[156:157], 0, s[2:3]
	global_load_dwordx4 v[210:213], v[244:245], off
	global_load_dwordx4 v[214:217], v[244:245], off offset:256
	s_mov_b32 s2, 0x48000
	v_lshl_add_u64 v[242:243], v[156:157], 0, s[2:3]
	global_load_dwordx4 v[218:221], v[242:243], off
	global_load_dwordx4 v[222:225], v[242:243], off offset:256
	s_mov_b32 s2, 0x50000
	v_lshl_add_u64 v[244:245], v[156:157], 0, s[2:3]
	global_load_dwordx4 v[226:229], v[244:245], off
	global_load_dwordx4 v[230:233], v[244:245], off offset:256
	s_mov_b32 s2, 0x58000
	v_lshl_add_u64 v[242:243], v[156:157], 0, s[2:3]
	global_load_dwordx4 v[234:237], v[242:243], off
	global_load_dwordx4 v[238:241], v[242:243], off offset:256
	s_waitcnt vmcnt(15)
	v_cvt_f32_f16_e32 v164, v166
	v_cvt_f32_f16_sdwa v165, v166 dst_sel:DWORD dst_unused:UNUSED_PAD src0_sel:WORD_1
	v_cvt_f32_f16_e32 v160, v167
	v_cvt_f32_f16_sdwa v161, v167 dst_sel:DWORD dst_unused:UNUSED_PAD src0_sel:WORD_1
	v_pk_add_f32 v[164:165], v[128:129], v[164:165]
	s_nop 0
	v_cvt_pk_f16_f32 v128, v164, v165
	v_pk_add_f32 v[160:161], v[130:131], v[160:161]
	v_cvt_f32_f16_e32 v130, v168
	v_cvt_f32_f16_sdwa v131, v168 dst_sel:DWORD dst_unused:UNUSED_PAD src0_sel:WORD_1
	v_cvt_f32_f16_e32 v162, v169
	v_cvt_f32_f16_sdwa v163, v169 dst_sel:DWORD dst_unused:UNUSED_PAD src0_sel:WORD_1
	v_cvt_pk_f16_f32 v129, v160, v161
	v_pk_add_f32 v[130:131], v[124:125], v[130:131]
	v_pk_add_f32 v[162:163], v[126:127], v[162:163]
	v_pk_mul_f32 v[124:125], v[130:131], v[130:131]
	v_cvt_pk_f16_f32 v130, v130, v131
	v_cvt_pk_f16_f32 v131, v162, v163
	global_store_dwordx4 v[156:157], v[128:131], off
	s_nop 0
	v_pk_mul_f32 v[126:127], v[162:163], v[162:163]
	v_pk_fma_f32 v[124:125], v[164:165], v[164:165], v[124:125]
	v_pk_fma_f32 v[126:127], v[160:161], v[160:161], v[126:127]
	s_waitcnt vmcnt(15)
	v_cvt_f32_f16_e32 v160, v170
	v_cvt_f32_f16_sdwa v161, v170 dst_sel:DWORD dst_unused:UNUSED_PAD src0_sel:WORD_1
	v_cvt_f32_f16_e32 v128, v171
	v_cvt_f32_f16_sdwa v129, v171 dst_sel:DWORD dst_unused:UNUSED_PAD src0_sel:WORD_1
	v_pk_add_f32 v[160:161], v[120:121], v[160:161]
	s_nop 0
	v_cvt_pk_f16_f32 v120, v160, v161
	v_pk_add_f32 v[128:129], v[122:123], v[128:129]
	v_cvt_f32_f16_e32 v122, v172
	v_cvt_f32_f16_sdwa v123, v172 dst_sel:DWORD dst_unused:UNUSED_PAD src0_sel:WORD_1
	v_cvt_pk_f16_f32 v121, v128, v129
	v_pk_add_f32 v[116:117], v[116:117], v[122:123]
	s_nop 0
	v_pk_mul_f32 v[122:123], v[116:117], v[116:117]
	s_nop 0
	v_pk_fma_f32 v[160:161], v[160:161], v[160:161], v[122:123]
	v_cvt_pk_f16_f32 v122, v116, v117
	v_cvt_f32_f16_e32 v116, v173
	v_cvt_f32_f16_sdwa v117, v173 dst_sel:DWORD dst_unused:UNUSED_PAD src0_sel:WORD_1
	v_add_f32_e32 v123, v124, v125
	v_add_f32_e32 v123, v126, v123
	v_add_f32_e32 v123, v127, v123
	v_pk_add_f32 v[116:117], v[118:119], v[116:117]
	v_add_f32_e32 v123, v160, v123
	v_pk_mul_f32 v[118:119], v[116:117], v[116:117]
	v_add_f32_e32 v123, v161, v123
	v_pk_fma_f32 v[118:119], v[128:129], v[128:129], v[118:119]
	s_nop 0
	v_add_f32_e32 v118, v118, v123
	v_add_f32_e32 v118, v119, v118
	v_cvt_pk_f16_f32 v123, v116, v117
	ds_swizzle_b32 v116, v118 offset:swizzle(SWAP,16)
	global_store_dwordx4 v[156:157], v[120:123], off offset:256
	s_waitcnt lgkmcnt(0)
	v_add_f32_e32 v116, v118, v116
	ds_bpermute_b32 v117, v0, v116
	s_and_saveexec_b64 s[22:23], s[6:7]
	s_cbranch_execz .LBB0_2383
	s_waitcnt lgkmcnt(0)
	v_add_f32_e32 v118, v116, v117
	v_lshlrev_b64 v[116:117], 6, v[2:3]
	v_lshl_add_u64 v[116:117], s[10:11], 0, v[116:117]
	v_lshl_add_u64 v[116:117], s[20:21], 2, v[116:117]
	s_lshl_b32 s92, s45, 2
	v_lshl_add_u64 v[116:117], v[116:117], 0, s[92:93]
	global_store_dword v[116:117], v118, off
; __device__ __forceinline__ float xor16(float v) { return __int_as_float(__builtin_amdgcn_ds_swizzle(__float_as_int(v), 0x401F)); }
;   __device__ __forceinline__ void operator()(const f32x4 (&acc)[2][2][4][2], const g8::Unit& u, int ui, int wr, int wc, int fr, int fq) const {
;     ...
;         const size_t row = (size_t)u.pm * 256 + 128 * ai + 64 * wr + 16 * m + fr;
;         const size_t base = row * DM + 256 * u.pn + 32 * wc + 8 * fq;
;         float ss = 0.f;
; #pragma unroll
;         for (int bj = 0; bj < 2; ++bj) {
;           const size_t idx = base + 128 * bj;
;           const h16x8 xv = *(const h16x8*)(xb + idx);
;           f32x4 x0 = acc[ai][bj][m][0], x1 = acc[ai][bj][m][1];
; #pragma unroll
;           for (int j = 0; j < 4; ++j) { x0[j] += (float)xv[j]; x1[j] += (float)xv[4 + j]; ss += x0[j] * x0[j] + x1[j] * x1[j]; }
;           if (final_out) {
;             __builtin_nontemporal_store(x0, (f32x4*)(xo + idx));
;             __builtin_nontemporal_store(x1, (f32x4*)(xo + idx + 4));
;           } else {
;             *(h16x8*)(xb + idx) = pack8(x0, x1);
;           }
;         }
;         ss += xor16(ss);
;         ss += __shfl_xor(ss, 32);
;         if (fq == 0) ssq[row * 16 + u.pn * 4 + wc] = ss;
.LBB0_2383:
	s_or_b64 exec, exec, s[22:23]
	v_or_b32_e32 v116, 16, v2
	s_waitcnt lgkmcnt(0)
	v_mov_b32_e32 v117, v3
	v_lshlrev_b64 v[118:119], 11, v[116:117]
	v_lshl_add_u64 v[118:119], s[0:1], 0, v[118:119]
	v_lshl_add_u64 v[118:119], v[154:155], 1, v[118:119]
	s_nop 0
	s_waitcnt vmcnt(15)
	v_cvt_f32_f16_e32 v124, v174
	v_cvt_f32_f16_sdwa v125, v174 dst_sel:DWORD dst_unused:UNUSED_PAD src0_sel:WORD_1
	v_cvt_f32_f16_e32 v120, v175
	v_cvt_f32_f16_sdwa v121, v175 dst_sel:DWORD dst_unused:UNUSED_PAD src0_sel:WORD_1
	v_pk_add_f32 v[124:125], v[112:113], v[124:125]
	s_nop 0
	v_cvt_pk_f16_f32 v112, v124, v125
	v_pk_add_f32 v[120:121], v[114:115], v[120:121]
	v_cvt_f32_f16_e32 v114, v176
	v_cvt_f32_f16_sdwa v115, v176 dst_sel:DWORD dst_unused:UNUSED_PAD src0_sel:WORD_1
	v_cvt_f32_f16_e32 v122, v177
	v_cvt_f32_f16_sdwa v123, v177 dst_sel:DWORD dst_unused:UNUSED_PAD src0_sel:WORD_1
	v_cvt_pk_f16_f32 v113, v120, v121
	v_pk_add_f32 v[114:115], v[108:109], v[114:115]
	v_pk_add_f32 v[122:123], v[110:111], v[122:123]
	v_pk_mul_f32 v[108:109], v[114:115], v[114:115]
	v_cvt_pk_f16_f32 v114, v114, v115
	v_cvt_pk_f16_f32 v115, v122, v123
	global_store_dwordx4 v[118:119], v[112:115], off
	s_nop 0
	v_pk_mul_f32 v[110:111], v[122:123], v[122:123]
	v_pk_fma_f32 v[108:109], v[124:125], v[124:125], v[108:109]
	v_pk_fma_f32 v[110:111], v[120:121], v[120:121], v[110:111]
	s_waitcnt vmcnt(15)
	v_cvt_f32_f16_e32 v120, v178
	v_cvt_f32_f16_sdwa v121, v178 dst_sel:DWORD dst_unused:UNUSED_PAD src0_sel:WORD_1
	v_cvt_f32_f16_e32 v112, v179
	v_cvt_f32_f16_sdwa v113, v179 dst_sel:DWORD dst_unused:UNUSED_PAD src0_sel:WORD_1
	v_pk_add_f32 v[120:121], v[104:105], v[120:121]
	s_nop 0
	v_cvt_pk_f16_f32 v104, v120, v121
	v_pk_add_f32 v[112:113], v[106:107], v[112:113]
	v_cvt_f32_f16_e32 v106, v180
	v_cvt_f32_f16_sdwa v107, v180 dst_sel:DWORD dst_unused:UNUSED_PAD src0_sel:WORD_1
	v_cvt_pk_f16_f32 v105, v112, v113
	v_pk_add_f32 v[100:101], v[100:101], v[106:107]
	s_nop 0
	v_pk_mul_f32 v[106:107], v[100:101], v[100:101]
	s_nop 0
	v_pk_fma_f32 v[120:121], v[120:121], v[120:121], v[106:107]
	v_cvt_pk_f16_f32 v106, v100, v101
	v_cvt_f32_f16_e32 v100, v181
	v_cvt_f32_f16_sdwa v101, v181 dst_sel:DWORD dst_unused:UNUSED_PAD src0_sel:WORD_1
	v_add_f32_e32 v107, v108, v109
	v_add_f32_e32 v107, v110, v107
	v_add_f32_e32 v107, v111, v107
	v_pk_add_f32 v[100:101], v[102:103], v[100:101]
	v_add_f32_e32 v107, v120, v107
	v_pk_mul_f32 v[102:103], v[100:101], v[100:101]
	v_add_f32_e32 v107, v121, v107
	v_pk_fma_f32 v[102:103], v[112:113], v[112:113], v[102:103]
	s_nop 0
	v_add_f32_e32 v102, v102, v107
	v_add_f32_e32 v102, v103, v102
	v_cvt_pk_f16_f32 v107, v100, v101
	ds_swizzle_b32 v100, v102 offset:swizzle(SWAP,16)
	global_store_dwordx4 v[118:119], v[104:107], off offset:256
	s_waitcnt lgkmcnt(0)
	v_add_f32_e32 v100, v102, v100
	ds_bpermute_b32 v101, v0, v100
	s_and_saveexec_b64 s[22:23], s[6:7]
	s_cbranch_execz .LBB0_2385
	s_waitcnt lgkmcnt(0)
	v_add_f32_e32 v102, v100, v101
	v_lshlrev_b64 v[100:101], 6, v[116:117]
	v_lshl_add_u64 v[100:101], s[10:11], 0, v[100:101]
	v_lshl_add_u64 v[100:101], s[20:21], 2, v[100:101]
	s_lshl_b32 s92, s45, 2
	v_lshl_add_u64 v[100:101], v[100:101], 0, s[92:93]
	global_store_dword v[100:101], v102, off
.LBB0_2385:
	s_or_b64 exec, exec, s[22:23]
	v_or_b32_e32 v100, 32, v2
	s_waitcnt lgkmcnt(0)
	v_mov_b32_e32 v101, v3
	v_lshlrev_b64 v[102:103], 11, v[100:101]
	v_lshl_add_u64 v[102:103], s[0:1], 0, v[102:103]
	v_lshl_add_u64 v[102:103], v[154:155], 1, v[102:103]
	s_nop 0
	s_waitcnt vmcnt(15)
	v_cvt_f32_f16_e32 v108, v182
	v_cvt_f32_f16_sdwa v109, v182 dst_sel:DWORD dst_unused:UNUSED_PAD src0_sel:WORD_1
	v_cvt_f32_f16_e32 v104, v183
	v_cvt_f32_f16_sdwa v105, v183 dst_sel:DWORD dst_unused:UNUSED_PAD src0_sel:WORD_1
	v_pk_add_f32 v[108:109], v[96:97], v[108:109]
	s_nop 0
	v_cvt_pk_f16_f32 v96, v108, v109
	v_pk_add_f32 v[104:105], v[98:99], v[104:105]
	v_cvt_f32_f16_e32 v98, v184
	v_cvt_f32_f16_sdwa v99, v184 dst_sel:DWORD dst_unused:UNUSED_PAD src0_sel:WORD_1
	v_cvt_f32_f16_e32 v106, v185
	v_cvt_f32_f16_sdwa v107, v185 dst_sel:DWORD dst_unused:UNUSED_PAD src0_sel:WORD_1
	v_cvt_pk_f16_f32 v97, v104, v105
	v_pk_add_f32 v[98:99], v[92:93], v[98:99]
	v_pk_add_f32 v[106:107], v[94:95], v[106:107]
	v_pk_mul_f32 v[92:93], v[98:99], v[98:99]
	v_cvt_pk_f16_f32 v98, v98, v99
	v_cvt_pk_f16_f32 v99, v106, v107
	global_store_dwordx4 v[102:103], v[96:99], off
	s_nop 0
	v_pk_mul_f32 v[94:95], v[106:107], v[106:107]
	v_pk_fma_f32 v[92:93], v[108:109], v[108:109], v[92:93]
	v_pk_fma_f32 v[94:95], v[104:105], v[104:105], v[94:95]
	s_waitcnt vmcnt(15)
	v_cvt_f32_f16_e32 v104, v186
	v_cvt_f32_f16_sdwa v105, v186 dst_sel:DWORD dst_unused:UNUSED_PAD src0_sel:WORD_1
	v_cvt_f32_f16_e32 v96, v187
	v_cvt_f32_f16_sdwa v97, v187 dst_sel:DWORD dst_unused:UNUSED_PAD src0_sel:WORD_1
	v_pk_add_f32 v[104:105], v[88:89], v[104:105]
	s_nop 0
	v_cvt_pk_f16_f32 v88, v104, v105
	v_pk_add_f32 v[96:97], v[90:91], v[96:97]
	v_cvt_f32_f16_e32 v90, v188
	v_cvt_f32_f16_sdwa v91, v188 dst_sel:DWORD dst_unused:UNUSED_PAD src0_sel:WORD_1
	v_cvt_pk_f16_f32 v89, v96, v97
	v_pk_add_f32 v[84:85], v[84:85], v[90:91]
	s_nop 0
	v_pk_mul_f32 v[90:91], v[84:85], v[84:85]
	s_nop 0
	v_pk_fma_f32 v[104:105], v[104:105], v[104:105], v[90:91]
	v_cvt_pk_f16_f32 v90, v84, v85
	v_cvt_f32_f16_e32 v84, v189
	v_cvt_f32_f16_sdwa v85, v189 dst_sel:DWORD dst_unused:UNUSED_PAD src0_sel:WORD_1
	v_add_f32_e32 v91, v92, v93
	v_add_f32_e32 v91, v94, v91
	v_add_f32_e32 v91, v95, v91
	v_pk_add_f32 v[84:85], v[86:87], v[84:85]
	v_add_f32_e32 v91, v104, v91
	v_pk_mul_f32 v[86:87], v[84:85], v[84:85]
	v_add_f32_e32 v91, v105, v91
	v_pk_fma_f32 v[86:87], v[96:97], v[96:97], v[86:87]
	s_nop 0
	v_add_f32_e32 v86, v86, v91
	v_add_f32_e32 v86, v87, v86
	v_cvt_pk_f16_f32 v91, v84, v85
	ds_swizzle_b32 v84, v86 offset:swizzle(SWAP,16)
	global_store_dwordx4 v[102:103], v[88:91], off offset:256
	s_waitcnt lgkmcnt(0)
	v_add_f32_e32 v84, v86, v84
	ds_bpermute_b32 v85, v0, v84
	s_and_saveexec_b64 s[22:23], s[6:7]
	s_cbranch_execz .LBB0_2387
	s_waitcnt lgkmcnt(0)
	v_add_f32_e32 v86, v84, v85
	v_lshlrev_b64 v[84:85], 6, v[100:101]
	v_lshl_add_u64 v[84:85], s[10:11], 0, v[84:85]
	v_lshl_add_u64 v[84:85], s[20:21], 2, v[84:85]
	s_lshl_b32 s92, s45, 2
	v_lshl_add_u64 v[84:85], v[84:85], 0, s[92:93]
	global_store_dword v[84:85], v86, off
; __device__ __forceinline__ float xor16(float v) { return __int_as_float(__builtin_amdgcn_ds_swizzle(__float_as_int(v), 0x401F)); }
;   __device__ __forceinline__ void operator()(const f32x4 (&acc)[2][2][4][2], const g8::Unit& u, int ui, int wr, int wc, int fr, int fq) const {
;     ...
;         const size_t row = (size_t)u.pm * 256 + 128 * ai + 64 * wr + 16 * m + fr;
;         const size_t base = row * DM + 256 * u.pn + 32 * wc + 8 * fq;
;         float ss = 0.f;
; #pragma unroll
;         for (int bj = 0; bj < 2; ++bj) {
;           const size_t idx = base + 128 * bj;
;           const h16x8 xv = *(const h16x8*)(xb + idx);
;           f32x4 x0 = acc[ai][bj][m][0], x1 = acc[ai][bj][m][1];
; #pragma unroll
;           for (int j = 0; j < 4; ++j) { x0[j] += (float)xv[j]; x1[j] += (float)xv[4 + j]; ss += x0[j] * x0[j] + x1[j] * x1[j]; }
;           if (final_out) {
;             __builtin_nontemporal_store(x0, (f32x4*)(xo + idx));
;             __builtin_nontemporal_store(x1, (f32x4*)(xo + idx + 4));
;           } else {
;             *(h16x8*)(xb + idx) = pack8(x0, x1);
;           }
;         }
;         ss += xor16(ss);
;         ss += __shfl_xor(ss, 32);
;         if (fq == 0) ssq[row * 16 + u.pn * 4 + wc] = ss;
.LBB0_2387:
	s_or_b64 exec, exec, s[22:23]
	v_or_b32_e32 v84, 48, v2
	s_waitcnt lgkmcnt(0)
	v_mov_b32_e32 v85, v3
	v_lshlrev_b64 v[86:87], 11, v[84:85]
	v_lshl_add_u64 v[86:87], s[0:1], 0, v[86:87]
	v_lshl_add_u64 v[86:87], v[154:155], 1, v[86:87]
	s_nop 0
	s_waitcnt vmcnt(15)
	v_cvt_f32_f16_e32 v92, v202
	v_cvt_f32_f16_sdwa v93, v202 dst_sel:DWORD dst_unused:UNUSED_PAD src0_sel:WORD_1
	v_cvt_f32_f16_e32 v88, v203
	v_cvt_f32_f16_sdwa v89, v203 dst_sel:DWORD dst_unused:UNUSED_PAD src0_sel:WORD_1
	v_pk_add_f32 v[92:93], v[80:81], v[92:93]
	s_nop 0
	v_cvt_pk_f16_f32 v80, v92, v93
	v_pk_add_f32 v[88:89], v[82:83], v[88:89]
	v_cvt_f32_f16_e32 v82, v204
	v_cvt_f32_f16_sdwa v83, v204 dst_sel:DWORD dst_unused:UNUSED_PAD src0_sel:WORD_1
	v_cvt_f32_f16_e32 v90, v205
	v_cvt_f32_f16_sdwa v91, v205 dst_sel:DWORD dst_unused:UNUSED_PAD src0_sel:WORD_1
	v_cvt_pk_f16_f32 v81, v88, v89
	v_pk_add_f32 v[82:83], v[76:77], v[82:83]
	v_pk_add_f32 v[90:91], v[78:79], v[90:91]
	v_pk_mul_f32 v[76:77], v[82:83], v[82:83]
	v_cvt_pk_f16_f32 v82, v82, v83
	v_cvt_pk_f16_f32 v83, v90, v91
	global_store_dwordx4 v[86:87], v[80:83], off
	s_nop 0
	v_pk_mul_f32 v[78:79], v[90:91], v[90:91]
	v_pk_fma_f32 v[76:77], v[92:93], v[92:93], v[76:77]
	v_pk_fma_f32 v[78:79], v[88:89], v[88:89], v[78:79]
	s_waitcnt vmcnt(15)
	v_cvt_f32_f16_e32 v88, v206
	v_cvt_f32_f16_sdwa v89, v206 dst_sel:DWORD dst_unused:UNUSED_PAD src0_sel:WORD_1
	v_cvt_f32_f16_e32 v80, v207
	v_cvt_f32_f16_sdwa v81, v207 dst_sel:DWORD dst_unused:UNUSED_PAD src0_sel:WORD_1
	v_pk_add_f32 v[88:89], v[72:73], v[88:89]
	s_nop 0
	v_cvt_pk_f16_f32 v72, v88, v89
	v_pk_add_f32 v[80:81], v[74:75], v[80:81]
	v_cvt_f32_f16_e32 v74, v208
	v_cvt_f32_f16_sdwa v75, v208 dst_sel:DWORD dst_unused:UNUSED_PAD src0_sel:WORD_1
	v_cvt_pk_f16_f32 v73, v80, v81
	v_pk_add_f32 v[68:69], v[68:69], v[74:75]
	s_nop 0
	v_pk_mul_f32 v[74:75], v[68:69], v[68:69]
	s_nop 0
	v_pk_fma_f32 v[88:89], v[88:89], v[88:89], v[74:75]
	v_cvt_pk_f16_f32 v74, v68, v69
	v_cvt_f32_f16_e32 v68, v209
	v_cvt_f32_f16_sdwa v69, v209 dst_sel:DWORD dst_unused:UNUSED_PAD src0_sel:WORD_1
	v_add_f32_e32 v75, v76, v77
	v_add_f32_e32 v75, v78, v75
	v_add_f32_e32 v75, v79, v75
	v_pk_add_f32 v[68:69], v[70:71], v[68:69]
	v_add_f32_e32 v75, v88, v75
	v_pk_mul_f32 v[70:71], v[68:69], v[68:69]
	v_add_f32_e32 v75, v89, v75
	v_pk_fma_f32 v[70:71], v[80:81], v[80:81], v[70:71]
	s_nop 0
	v_add_f32_e32 v70, v70, v75
	v_add_f32_e32 v70, v71, v70
	v_cvt_pk_f16_f32 v75, v68, v69
	ds_swizzle_b32 v68, v70 offset:swizzle(SWAP,16)
	global_store_dwordx4 v[86:87], v[72:75], off offset:256
	s_waitcnt lgkmcnt(0)
	v_add_f32_e32 v68, v70, v68
	ds_bpermute_b32 v69, v0, v68
	s_and_saveexec_b64 s[22:23], s[6:7]
	s_cbranch_execz .LBB0_2389
	s_waitcnt lgkmcnt(0)
	v_add_f32_e32 v70, v68, v69
	v_lshlrev_b64 v[68:69], 6, v[84:85]
	v_lshl_add_u64 v[68:69], s[10:11], 0, v[68:69]
	v_lshl_add_u64 v[68:69], s[20:21], 2, v[68:69]
	s_lshl_b32 s92, s45, 2
	v_lshl_add_u64 v[68:69], v[68:69], 0, s[92:93]
	global_store_dword v[68:69], v70, off
.LBB0_2389:
	s_or_b64 exec, exec, s[22:23]
	s_waitcnt lgkmcnt(0)
	v_lshl_add_u64 v[68:69], v[2:3], 0, s[94:95]
	v_lshlrev_b64 v[70:71], 11, v[68:69]
	v_lshl_add_u64 v[70:71], s[0:1], 0, v[70:71]
	v_lshl_add_u64 v[70:71], v[154:155], 1, v[70:71]
	s_nop 0
	s_waitcnt vmcnt(15)
	v_cvt_f32_f16_e32 v76, v210
	v_cvt_f32_f16_sdwa v77, v210 dst_sel:DWORD dst_unused:UNUSED_PAD src0_sel:WORD_1
	v_cvt_f32_f16_e32 v72, v211
	v_cvt_f32_f16_sdwa v73, v211 dst_sel:DWORD dst_unused:UNUSED_PAD src0_sel:WORD_1
	v_pk_add_f32 v[76:77], v[64:65], v[76:77]
	s_nop 0
	v_cvt_pk_f16_f32 v64, v76, v77
	v_pk_add_f32 v[72:73], v[66:67], v[72:73]
	v_cvt_f32_f16_e32 v66, v212
	v_cvt_f32_f16_sdwa v67, v212 dst_sel:DWORD dst_unused:UNUSED_PAD src0_sel:WORD_1
	v_cvt_f32_f16_e32 v74, v213
	v_cvt_f32_f16_sdwa v75, v213 dst_sel:DWORD dst_unused:UNUSED_PAD src0_sel:WORD_1
	v_cvt_pk_f16_f32 v65, v72, v73
	v_pk_add_f32 v[66:67], v[60:61], v[66:67]
	v_pk_add_f32 v[74:75], v[62:63], v[74:75]
	v_pk_mul_f32 v[60:61], v[66:67], v[66:67]
	v_cvt_pk_f16_f32 v66, v66, v67
	v_cvt_pk_f16_f32 v67, v74, v75
	global_store_dwordx4 v[70:71], v[64:67], off
	s_nop 0
	v_pk_mul_f32 v[62:63], v[74:75], v[74:75]
	v_pk_fma_f32 v[60:61], v[76:77], v[76:77], v[60:61]
	v_pk_fma_f32 v[62:63], v[72:73], v[72:73], v[62:63]
	s_waitcnt vmcnt(15)
	v_cvt_f32_f16_e32 v72, v214
	v_cvt_f32_f16_sdwa v73, v214 dst_sel:DWORD dst_unused:UNUSED_PAD src0_sel:WORD_1
	v_cvt_f32_f16_e32 v64, v215
	v_cvt_f32_f16_sdwa v65, v215 dst_sel:DWORD dst_unused:UNUSED_PAD src0_sel:WORD_1
	v_pk_add_f32 v[72:73], v[56:57], v[72:73]
	s_nop 0
	v_cvt_pk_f16_f32 v56, v72, v73
	v_pk_add_f32 v[64:65], v[58:59], v[64:65]
	v_cvt_f32_f16_e32 v58, v216
	v_cvt_f32_f16_sdwa v59, v216 dst_sel:DWORD dst_unused:UNUSED_PAD src0_sel:WORD_1
	v_cvt_pk_f16_f32 v57, v64, v65
	v_pk_add_f32 v[52:53], v[52:53], v[58:59]
	s_nop 0
	v_pk_mul_f32 v[58:59], v[52:53], v[52:53]
	s_nop 0
	v_pk_fma_f32 v[72:73], v[72:73], v[72:73], v[58:59]
	v_cvt_pk_f16_f32 v58, v52, v53
	v_cvt_f32_f16_e32 v52, v217
	v_cvt_f32_f16_sdwa v53, v217 dst_sel:DWORD dst_unused:UNUSED_PAD src0_sel:WORD_1
	v_add_f32_e32 v59, v60, v61
	v_add_f32_e32 v59, v62, v59
	v_add_f32_e32 v59, v63, v59
	v_pk_add_f32 v[52:53], v[54:55], v[52:53]
	v_add_f32_e32 v59, v72, v59
	v_pk_mul_f32 v[54:55], v[52:53], v[52:53]
	v_add_f32_e32 v59, v73, v59
	v_pk_fma_f32 v[54:55], v[64:65], v[64:65], v[54:55]
	s_nop 0
	v_add_f32_e32 v54, v54, v59
	v_add_f32_e32 v54, v55, v54
	v_cvt_pk_f16_f32 v59, v52, v53
	ds_swizzle_b32 v52, v54 offset:swizzle(SWAP,16)
	global_store_dwordx4 v[70:71], v[56:59], off offset:256
	s_waitcnt lgkmcnt(0)
	v_add_f32_e32 v52, v54, v52
	ds_bpermute_b32 v53, v0, v52
	s_and_saveexec_b64 s[22:23], s[6:7]
	s_cbranch_execz .LBB0_2391
	s_waitcnt lgkmcnt(0)
	v_add_f32_e32 v54, v52, v53
	v_lshlrev_b64 v[52:53], 6, v[68:69]
	v_lshl_add_u64 v[52:53], s[10:11], 0, v[52:53]
	v_lshl_add_u64 v[52:53], s[20:21], 2, v[52:53]
	s_lshl_b32 s92, s45, 2
	v_lshl_add_u64 v[52:53], v[52:53], 0, s[92:93]
	global_store_dword v[52:53], v54, off
; __device__ __forceinline__ float xor16(float v) { return __int_as_float(__builtin_amdgcn_ds_swizzle(__float_as_int(v), 0x401F)); }
;   __device__ __forceinline__ void operator()(const f32x4 (&acc)[2][2][4][2], const g8::Unit& u, int ui, int wr, int wc, int fr, int fq) const {
;     ...
;         const size_t row = (size_t)u.pm * 256 + 128 * ai + 64 * wr + 16 * m + fr;
;         const size_t base = row * DM + 256 * u.pn + 32 * wc + 8 * fq;
;         float ss = 0.f;
; #pragma unroll
;         for (int bj = 0; bj < 2; ++bj) {
;           const size_t idx = base + 128 * bj;
;           const h16x8 xv = *(const h16x8*)(xb + idx);
;           f32x4 x0 = acc[ai][bj][m][0], x1 = acc[ai][bj][m][1];
; #pragma unroll
;           for (int j = 0; j < 4; ++j) { x0[j] += (float)xv[j]; x1[j] += (float)xv[4 + j]; ss += x0[j] * x0[j] + x1[j] * x1[j]; }
;           if (final_out) {
;             __builtin_nontemporal_store(x0, (f32x4*)(xo + idx));
;             __builtin_nontemporal_store(x1, (f32x4*)(xo + idx + 4));
;           } else {
;             *(h16x8*)(xb + idx) = pack8(x0, x1);
;           }
;         }
;         ss += xor16(ss);
;         ss += __shfl_xor(ss, 32);
;         if (fq == 0) ssq[row * 16 + u.pn * 4 + wc] = ss;
.LBB0_2391:
	s_or_b64 exec, exec, s[22:23]
	s_mov_b64 s[2:3], 0x90
	s_waitcnt lgkmcnt(0)
	v_lshl_add_u64 v[52:53], v[2:3], 0, s[2:3]
	v_lshlrev_b64 v[54:55], 11, v[52:53]
	v_lshl_add_u64 v[54:55], s[0:1], 0, v[54:55]
	v_lshl_add_u64 v[54:55], v[154:155], 1, v[54:55]
	s_nop 0
	s_waitcnt vmcnt(15)
	v_cvt_f32_f16_e32 v60, v218
	v_cvt_f32_f16_sdwa v61, v218 dst_sel:DWORD dst_unused:UNUSED_PAD src0_sel:WORD_1
	v_cvt_f32_f16_e32 v56, v219
	v_cvt_f32_f16_sdwa v57, v219 dst_sel:DWORD dst_unused:UNUSED_PAD src0_sel:WORD_1
	v_pk_add_f32 v[60:61], v[48:49], v[60:61]
	s_nop 0
	v_cvt_pk_f16_f32 v48, v60, v61
	v_pk_add_f32 v[56:57], v[50:51], v[56:57]
	v_cvt_f32_f16_e32 v50, v220
	v_cvt_f32_f16_sdwa v51, v220 dst_sel:DWORD dst_unused:UNUSED_PAD src0_sel:WORD_1
	v_cvt_f32_f16_e32 v58, v221
	v_cvt_f32_f16_sdwa v59, v221 dst_sel:DWORD dst_unused:UNUSED_PAD src0_sel:WORD_1
	v_cvt_pk_f16_f32 v49, v56, v57
	v_pk_add_f32 v[50:51], v[44:45], v[50:51]
	v_pk_add_f32 v[58:59], v[46:47], v[58:59]
	v_pk_mul_f32 v[44:45], v[50:51], v[50:51]
	v_cvt_pk_f16_f32 v50, v50, v51
	v_cvt_pk_f16_f32 v51, v58, v59
	global_store_dwordx4 v[54:55], v[48:51], off
	s_nop 0
	v_pk_mul_f32 v[46:47], v[58:59], v[58:59]
	v_pk_fma_f32 v[44:45], v[60:61], v[60:61], v[44:45]
	v_pk_fma_f32 v[46:47], v[56:57], v[56:57], v[46:47]
	s_waitcnt vmcnt(15)
	v_cvt_f32_f16_e32 v56, v222
	v_cvt_f32_f16_sdwa v57, v222 dst_sel:DWORD dst_unused:UNUSED_PAD src0_sel:WORD_1
	v_cvt_f32_f16_e32 v48, v223
	v_cvt_f32_f16_sdwa v49, v223 dst_sel:DWORD dst_unused:UNUSED_PAD src0_sel:WORD_1
	v_pk_add_f32 v[56:57], v[40:41], v[56:57]
	s_nop 0
	v_cvt_pk_f16_f32 v40, v56, v57
	v_pk_add_f32 v[48:49], v[42:43], v[48:49]
	v_cvt_f32_f16_e32 v42, v224
	v_cvt_f32_f16_sdwa v43, v224 dst_sel:DWORD dst_unused:UNUSED_PAD src0_sel:WORD_1
	v_cvt_pk_f16_f32 v41, v48, v49
	v_pk_add_f32 v[36:37], v[36:37], v[42:43]
	s_nop 0
	v_pk_mul_f32 v[42:43], v[36:37], v[36:37]
	s_nop 0
	v_pk_fma_f32 v[56:57], v[56:57], v[56:57], v[42:43]
	v_cvt_pk_f16_f32 v42, v36, v37
	v_cvt_f32_f16_e32 v36, v225
	v_cvt_f32_f16_sdwa v37, v225 dst_sel:DWORD dst_unused:UNUSED_PAD src0_sel:WORD_1
	v_add_f32_e32 v43, v44, v45
	v_add_f32_e32 v43, v46, v43
	v_add_f32_e32 v43, v47, v43
	v_pk_add_f32 v[36:37], v[38:39], v[36:37]
	v_add_f32_e32 v43, v56, v43
	v_pk_mul_f32 v[38:39], v[36:37], v[36:37]
	v_add_f32_e32 v43, v57, v43
	v_pk_fma_f32 v[38:39], v[48:49], v[48:49], v[38:39]
	s_nop 0
	v_add_f32_e32 v38, v38, v43
	v_add_f32_e32 v38, v39, v38
	v_cvt_pk_f16_f32 v43, v36, v37
	ds_swizzle_b32 v36, v38 offset:swizzle(SWAP,16)
	global_store_dwordx4 v[54:55], v[40:43], off offset:256
	s_waitcnt lgkmcnt(0)
	v_add_f32_e32 v36, v38, v36
	ds_bpermute_b32 v37, v0, v36
	s_and_saveexec_b64 s[22:23], s[6:7]
	s_cbranch_execz .LBB0_2393
	s_waitcnt lgkmcnt(0)
	v_add_f32_e32 v38, v36, v37
	v_lshlrev_b64 v[36:37], 6, v[52:53]
	v_lshl_add_u64 v[36:37], s[10:11], 0, v[36:37]
	v_lshl_add_u64 v[36:37], s[20:21], 2, v[36:37]
	s_lshl_b32 s92, s45, 2
	v_lshl_add_u64 v[36:37], v[36:37], 0, s[92:93]
	global_store_dword v[36:37], v38, off
; __device__ __forceinline__ float xor16(float v) { return __int_as_float(__builtin_amdgcn_ds_swizzle(__float_as_int(v), 0x401F)); }
;   __device__ __forceinline__ void operator()(const f32x4 (&acc)[2][2][4][2], const g8::Unit& u, int ui, int wr, int wc, int fr, int fq) const {
;     ...
;         const size_t row = (size_t)u.pm * 256 + 128 * ai + 64 * wr + 16 * m + fr;
;         const size_t base = row * DM + 256 * u.pn + 32 * wc + 8 * fq;
;         float ss = 0.f;
; #pragma unroll
;         for (int bj = 0; bj < 2; ++bj) {
;           const size_t idx = base + 128 * bj;
;           const h16x8 xv = *(const h16x8*)(xb + idx);
;           f32x4 x0 = acc[ai][bj][m][0], x1 = acc[ai][bj][m][1];
; #pragma unroll
;           for (int j = 0; j < 4; ++j) { x0[j] += (float)xv[j]; x1[j] += (float)xv[4 + j]; ss += x0[j] * x0[j] + x1[j] * x1[j]; }
;           if (final_out) {
;             __builtin_nontemporal_store(x0, (f32x4*)(xo + idx));
;             __builtin_nontemporal_store(x1, (f32x4*)(xo + idx + 4));
;           } else {
;             *(h16x8*)(xb + idx) = pack8(x0, x1);
;           }
;         }
;         ss += xor16(ss);
;         ss += __shfl_xor(ss, 32);
;         if (fq == 0) ssq[row * 16 + u.pn * 4 + wc] = ss;
.LBB0_2393:
	s_or_b64 exec, exec, s[22:23]
	s_mov_b64 s[2:3], 0xa0
	s_waitcnt lgkmcnt(0)
	v_lshl_add_u64 v[36:37], v[2:3], 0, s[2:3]
	v_lshlrev_b64 v[38:39], 11, v[36:37]
	v_lshl_add_u64 v[38:39], s[0:1], 0, v[38:39]
	v_lshl_add_u64 v[38:39], v[154:155], 1, v[38:39]
	s_nop 0
	s_waitcnt vmcnt(15)
	v_cvt_f32_f16_e32 v44, v226
	v_cvt_f32_f16_sdwa v45, v226 dst_sel:DWORD dst_unused:UNUSED_PAD src0_sel:WORD_1
	v_cvt_f32_f16_e32 v40, v227
	v_cvt_f32_f16_sdwa v41, v227 dst_sel:DWORD dst_unused:UNUSED_PAD src0_sel:WORD_1
	v_pk_add_f32 v[44:45], v[32:33], v[44:45]
	s_nop 0
	v_cvt_pk_f16_f32 v32, v44, v45
	v_pk_add_f32 v[40:41], v[34:35], v[40:41]
	v_cvt_f32_f16_e32 v34, v228
	v_cvt_f32_f16_sdwa v35, v228 dst_sel:DWORD dst_unused:UNUSED_PAD src0_sel:WORD_1
	v_cvt_f32_f16_e32 v42, v229
	v_cvt_f32_f16_sdwa v43, v229 dst_sel:DWORD dst_unused:UNUSED_PAD src0_sel:WORD_1
	v_cvt_pk_f16_f32 v33, v40, v41
	v_pk_add_f32 v[34:35], v[28:29], v[34:35]
	v_pk_add_f32 v[42:43], v[30:31], v[42:43]
	v_pk_mul_f32 v[28:29], v[34:35], v[34:35]
	v_cvt_pk_f16_f32 v34, v34, v35
	v_cvt_pk_f16_f32 v35, v42, v43
	global_store_dwordx4 v[38:39], v[32:35], off
	s_nop 0
	v_pk_mul_f32 v[30:31], v[42:43], v[42:43]
	v_pk_fma_f32 v[28:29], v[44:45], v[44:45], v[28:29]
	v_pk_fma_f32 v[30:31], v[40:41], v[40:41], v[30:31]
	s_waitcnt vmcnt(15)
	v_cvt_f32_f16_e32 v40, v230
	v_cvt_f32_f16_sdwa v41, v230 dst_sel:DWORD dst_unused:UNUSED_PAD src0_sel:WORD_1
	v_cvt_f32_f16_e32 v32, v231
	v_cvt_f32_f16_sdwa v33, v231 dst_sel:DWORD dst_unused:UNUSED_PAD src0_sel:WORD_1
	v_pk_add_f32 v[40:41], v[24:25], v[40:41]
	s_nop 0
	v_cvt_pk_f16_f32 v24, v40, v41
	v_pk_add_f32 v[32:33], v[26:27], v[32:33]
	v_cvt_f32_f16_e32 v26, v232
	v_cvt_f32_f16_sdwa v27, v232 dst_sel:DWORD dst_unused:UNUSED_PAD src0_sel:WORD_1
	v_cvt_pk_f16_f32 v25, v32, v33
	v_pk_add_f32 v[20:21], v[20:21], v[26:27]
	s_nop 0
	v_pk_mul_f32 v[26:27], v[20:21], v[20:21]
	s_nop 0
	v_pk_fma_f32 v[40:41], v[40:41], v[40:41], v[26:27]
	v_cvt_pk_f16_f32 v26, v20, v21
	v_cvt_f32_f16_e32 v20, v233
	v_cvt_f32_f16_sdwa v21, v233 dst_sel:DWORD dst_unused:UNUSED_PAD src0_sel:WORD_1
	v_add_f32_e32 v27, v28, v29
	v_add_f32_e32 v27, v30, v27
	v_add_f32_e32 v27, v31, v27
	v_pk_add_f32 v[20:21], v[22:23], v[20:21]
	v_add_f32_e32 v27, v40, v27
	v_pk_mul_f32 v[22:23], v[20:21], v[20:21]
	v_add_f32_e32 v27, v41, v27
	v_pk_fma_f32 v[22:23], v[32:33], v[32:33], v[22:23]
	s_nop 0
	v_add_f32_e32 v22, v22, v27
	v_add_f32_e32 v22, v23, v22
	v_cvt_pk_f16_f32 v27, v20, v21
	ds_swizzle_b32 v20, v22 offset:swizzle(SWAP,16)
	global_store_dwordx4 v[38:39], v[24:27], off offset:256
	s_waitcnt lgkmcnt(0)
	v_add_f32_e32 v20, v22, v20
	ds_bpermute_b32 v21, v0, v20
	s_and_saveexec_b64 s[22:23], s[6:7]
	s_cbranch_execz .LBB0_2395
	s_waitcnt lgkmcnt(0)
	v_add_f32_e32 v22, v20, v21
	v_lshlrev_b64 v[20:21], 6, v[36:37]
	v_lshl_add_u64 v[20:21], s[10:11], 0, v[20:21]
	v_lshl_add_u64 v[20:21], s[20:21], 2, v[20:21]
	s_lshl_b32 s92, s45, 2
	v_lshl_add_u64 v[20:21], v[20:21], 0, s[92:93]
	global_store_dword v[20:21], v22, off
.LBB0_2395:
	s_or_b64 exec, exec, s[22:23]
	s_mov_b64 s[2:3], 0xb0
	v_lshl_add_u64 v[2:3], v[2:3], 0, s[2:3]
	s_waitcnt lgkmcnt(0)
	v_lshlrev_b64 v[20:21], 11, v[2:3]
	v_lshl_add_u64 v[20:21], s[0:1], 0, v[20:21]
	v_lshl_add_u64 v[20:21], v[154:155], 1, v[20:21]
	s_nop 0
	s_waitcnt vmcnt(15)
	v_cvt_f32_f16_e32 v26, v234
	v_cvt_f32_f16_sdwa v27, v234 dst_sel:DWORD dst_unused:UNUSED_PAD src0_sel:WORD_1
	v_cvt_f32_f16_e32 v22, v235
	v_cvt_f32_f16_sdwa v23, v235 dst_sel:DWORD dst_unused:UNUSED_PAD src0_sel:WORD_1
	v_pk_add_f32 v[26:27], v[16:17], v[26:27]
	s_nop 0
	v_cvt_pk_f16_f32 v16, v26, v27
	v_pk_add_f32 v[22:23], v[18:19], v[22:23]
	v_cvt_f32_f16_e32 v18, v236
	v_cvt_f32_f16_sdwa v19, v236 dst_sel:DWORD dst_unused:UNUSED_PAD src0_sel:WORD_1
	v_cvt_f32_f16_e32 v24, v237
	v_cvt_f32_f16_sdwa v25, v237 dst_sel:DWORD dst_unused:UNUSED_PAD src0_sel:WORD_1
	v_cvt_pk_f16_f32 v17, v22, v23
	v_pk_add_f32 v[18:19], v[12:13], v[18:19]
	v_pk_add_f32 v[24:25], v[14:15], v[24:25]
	v_pk_mul_f32 v[12:13], v[18:19], v[18:19]
	v_cvt_pk_f16_f32 v18, v18, v19
	v_cvt_pk_f16_f32 v19, v24, v25
	global_store_dwordx4 v[20:21], v[16:19], off
	s_nop 0
	v_pk_mul_f32 v[14:15], v[24:25], v[24:25]
	v_pk_fma_f32 v[12:13], v[26:27], v[26:27], v[12:13]
	v_pk_fma_f32 v[14:15], v[22:23], v[22:23], v[14:15]
	s_waitcnt vmcnt(15)
	v_cvt_f32_f16_e32 v22, v238
	v_cvt_f32_f16_sdwa v23, v238 dst_sel:DWORD dst_unused:UNUSED_PAD src0_sel:WORD_1
	v_cvt_f32_f16_e32 v16, v239
	v_cvt_f32_f16_sdwa v17, v239 dst_sel:DWORD dst_unused:UNUSED_PAD src0_sel:WORD_1
	v_pk_add_f32 v[22:23], v[8:9], v[22:23]
	s_nop 0
	v_cvt_pk_f16_f32 v8, v22, v23
	v_pk_add_f32 v[16:17], v[10:11], v[16:17]
	v_cvt_f32_f16_e32 v10, v240
	v_cvt_f32_f16_sdwa v11, v240 dst_sel:DWORD dst_unused:UNUSED_PAD src0_sel:WORD_1
	v_cvt_pk_f16_f32 v9, v16, v17
	v_pk_add_f32 v[4:5], v[4:5], v[10:11]
	s_nop 0
	v_pk_mul_f32 v[10:11], v[4:5], v[4:5]
	s_nop 0
	v_pk_fma_f32 v[22:23], v[22:23], v[22:23], v[10:11]
	v_cvt_pk_f16_f32 v10, v4, v5
	v_cvt_f32_f16_e32 v4, v241
	v_cvt_f32_f16_sdwa v5, v241 dst_sel:DWORD dst_unused:UNUSED_PAD src0_sel:WORD_1
	v_add_f32_e32 v11, v12, v13
	v_add_f32_e32 v11, v14, v11
	v_add_f32_e32 v11, v15, v11
	v_pk_add_f32 v[4:5], v[6:7], v[4:5]
	v_add_f32_e32 v11, v22, v11
	v_pk_mul_f32 v[6:7], v[4:5], v[4:5]
	v_add_f32_e32 v11, v23, v11
	v_pk_fma_f32 v[6:7], v[16:17], v[16:17], v[6:7]
	s_nop 0
	v_add_f32_e32 v6, v6, v11
	v_add_f32_e32 v6, v7, v6
	v_cvt_pk_f16_f32 v11, v4, v5
	ds_swizzle_b32 v4, v6 offset:swizzle(SWAP,16)
	global_store_dwordx4 v[20:21], v[8:11], off offset:256
	s_waitcnt lgkmcnt(0)
	v_add_f32_e32 v4, v6, v4
	ds_bpermute_b32 v0, v0, v4
	s_and_saveexec_b64 s[22:23], s[6:7]
	s_cbranch_execz .LBB0_2370
	v_lshlrev_b64 v[2:3], 6, v[2:3]
	v_lshl_add_u64 v[2:3], s[10:11], 0, v[2:3]
	v_lshl_add_u64 v[2:3], s[20:21], 2, v[2:3]
	s_lshl_b32 s92, s45, 2
	s_waitcnt lgkmcnt(0)
	v_add_f32_e32 v0, v4, v0
	v_lshl_add_u64 v[2:3], v[2:3], 0, s[92:93]
	global_store_dword v[2:3], v0, off
	s_branch .LBB0_2370
